# attention loop: 18 v_add_f32_e64 with plain VGPR operands re-encoded as e32
# speedup vs baseline: 1.0024x; 1.0017x over previous
; #define LAS __attribute__((address_space(3)))
; __device__ __forceinline__ float ex2(float x) { return __builtin_amdgcn_exp2f(x); }
; template <bool SAFE>
; __device__ void phase_attn(const Params& p, const bf16_t* Qall, const bf16_t* Kall, const bf16_t* Vt, bf16_t* CAT, LAS unsigned char* lds) {
;     ...
;         const bf16x8 ka = *(const LAS bf16x8*)(kb_ + (r * KROW + 16 * c + 8 * hh) * 2);
;         const bf16x8 kb2 = *(const LAS bf16x8*)(kb_ + ((32 + r) * KROW + 16 * c + 8 * hh) * 2);
; #pragma unroll
;         for (int qb = 0; qb < 2; ++qb) {
;           s[qb][0] = __builtin_amdgcn_mfma_f32_32x32x16_bf16(ka, qf[qb][c], s[qb][0], 0, 0, 0);
;           s[qb][1] = __builtin_amdgcn_mfma_f32_32x32x16_bf16(kb2, qf[qb][c], s[qb][1], 0, 0, 0);
;         }
;       }
; #pragma unroll
;       for (int qb = 0; qb < 2; ++qb) {
;         if (SAFE) {
;           float mx = fmaxf(s[qb][0][0], s[qb][1][0]);
; #pragma unroll
;           for (int e = 1; e < 16; ++e) mx = fmaxf(mx, fmaxf(s[qb][0][e], s[qb][1][e]));
;           mx = fmaxf(mx, __shfl_xor(mx, 32));
;           const bool need = (i == 0) || (mx - mrun[qb] > 8.f);
;           if (__builtin_amdgcn_ballot_w64(need) != 0ull) {
;             const float nm = need ? mx : mrun[qb];
;             const float alpha = (i == 0) ? 1.f : ex2(mrun[qb] - nm);
;             mrun[qb] = nm; lrun[qb] *= alpha;
; #pragma unroll
;             for (int e = 0; e < 16; ++e) { o[qb][0][e] *= alpha; o[qb][1][e] *= alpha; }
;           }
;         }
;         f32x2 ps2 = {0.f, 0.f};
;         const f32x2 m2 = {mrun[qb], mrun[qb]};
; #pragma unroll
;         for (int kb = 0; kb < 2; ++kb)
; #pragma unroll
;           for (int e = 0; e < 16; e += 2) {
;             f32x2 t = {s[qb][kb][e], s[qb][kb][e + 1]};
;             if (SAFE) t = t - m2;
;             t.x = ex2(t.x); t.y = ex2(t.y);
;             ps2 += t;
;             s[qb][kb][e] = t.x; s[qb][kb][e + 1] = t.y;
;           }
;         lrun[qb] += ps2.x + ps2.y;
;     ...
;       for (int kb = 0; kb < 2; ++kb)
; #pragma unroll
;         for (int t = 0; t < 2; ++t) {
;           const int kofs = 32 * kb + 16 * t + 4 * hh;
;           u32x4 va, vb2;
;           { const u32x2 lo = *(const LAS u32x2*)(vb_ + (r * VROW + kofs) * 2), hi = *(const LAS u32x2*)(vb_ + (r * VROW + kofs + 8) * 2); va.x = lo.x; va.y = lo.y; va.z = hi.x; va.w = hi.y; }
.LBB0_1258:
	s_bitcmp1_b32 s51, 0
	s_cselect_b32 s28, 0x5800, 0
	s_add_i32 s28, s28, 0
	v_add_u32_e32 v186, s28, v179
	ds_read_b128 v[64:67], v186
	ds_read_b128 v[206:209], v186 offset:32
	ds_read_b128 v[68:71], v186 offset:6656
	ds_read_b128 v[210:213], v186 offset:6688
	s_mov_b32 s51, s50
	s_waitcnt lgkmcnt(0)
	v_mfma_f32_32x32x16_bf16 v[112:127], v[64:67], v[164:167], 0
	v_mfma_f32_32x32x16_bf16 v[96:111], v[68:71], v[164:167], 0
	v_mfma_f32_32x32x16_bf16 v[80:95], v[64:67], v[172:175], 0
	v_mfma_f32_32x32x16_bf16 v[64:79], v[68:71], v[172:175], 0
	v_mfma_f32_32x32x16_bf16 v[112:127], v[206:209], v[160:163], v[112:127]
	v_mfma_f32_32x32x16_bf16 v[96:111], v[210:213], v[160:163], v[96:111]
	v_mfma_f32_32x32x16_bf16 v[80:95], v[206:209], v[168:171], v[80:95]
	v_mfma_f32_32x32x16_bf16 v[64:79], v[210:213], v[168:171], v[64:79]
	ds_read_b128 v[206:209], v186 offset:64
	ds_read_b128 v[210:213], v186 offset:96
	ds_read_b128 v[214:217], v186 offset:6720
	ds_read_b128 v[218:221], v186 offset:6752
	s_waitcnt lgkmcnt(0)
	v_mfma_f32_32x32x16_bf16 v[112:127], v[206:209], v[152:155], v[112:127]
	v_mfma_f32_32x32x16_bf16 v[112:127], v[210:213], v[148:151], v[112:127]
	v_mfma_f32_32x32x16_bf16 v[96:111], v[214:217], v[152:155], v[96:111]
	v_mfma_f32_32x32x16_bf16 v[80:95], v[206:209], v[156:159], v[80:95]
	v_mfma_f32_32x32x16_bf16 v[64:79], v[214:217], v[156:159], v[64:79]
	ds_read_b128 v[206:209], v186 offset:128
	ds_read_b128 v[214:217], v186 offset:160
	ds_read_b128 v[222:225], v186 offset:6784
	ds_read_b128 v[226:229], v186 offset:6816
	s_waitcnt lgkmcnt(0)
	v_mfma_f32_32x32x16_bf16 v[112:127], v[206:209], v[144:147], v[112:127]
	v_mfma_f32_32x32x16_bf16 v[96:111], v[218:221], v[148:151], v[96:111]
	v_mfma_f32_32x32x16_bf16 v[112:127], v[214:217], v[140:143], v[112:127]
	v_mfma_f32_32x32x16_bf16 v[96:111], v[222:225], v[144:147], v[96:111]
	s_nop 10
	v_exp_f32_e32 v230, v112
	v_exp_f32_e32 v231, v113
	v_exp_f32_e32 v232, v114
	v_exp_f32_e32 v233, v115
	v_exp_f32_e32 v234, v116
	v_exp_f32_e32 v235, v117
	v_exp_f32_e32 v236, v118
	v_mfma_f32_32x32x16_bf16 v[80:95], v[210:213], v[136:139], v[80:95]
	v_exp_f32_e32 v237, v119
	v_add_f32_e32 v112, 0, v230
	v_add_f32_e32 v113, 0, v231
	v_exp_f32_e32 v238, v120
	v_exp_f32_e32 v239, v121
	v_add_f32_e32 v112, v232, v112
	v_add_f32_e32 v113, v233, v113
	v_exp_f32_e32 v240, v122
	v_exp_f32_e32 v241, v123
	v_mfma_f32_32x32x16_bf16 v[96:111], v[226:229], v[140:143], v[96:111]
	v_add_f32_e32 v112, v234, v112
	v_add_f32_e32 v113, v235, v113
	v_exp_f32_e32 v124, v124
	v_exp_f32_e32 v125, v125
	v_add_f32_e32 v112, v236, v112
	v_add_f32_e32 v113, v237, v113
	v_exp_f32_e32 v126, v126
	v_add_f32_e32 v112, v238, v112
	v_add_f32_e32 v113, v239, v113
	v_exp_f32_e32 v127, v127
	v_mfma_f32_32x32x16_bf16 v[80:95], v[206:209], v[132:135], v[80:95]
	v_add_f32_e32 v112, v240, v112
	v_add_f32_e32 v113, v241, v113
	s_nop 0
	v_exp_f32_e32 v114, v98
	v_add_f32_e32 v118, v124, v112
	v_add_f32_e32 v119, v125, v113
	v_exp_f32_e32 v112, v96
	v_exp_f32_e32 v113, v97
	v_exp_f32_e32 v115, v99
	v_exp_f32_e32 v116, v100
	v_exp_f32_e32 v117, v101
	v_add_f32_e32 v96, v126, v118
	v_add_f32_e32 v97, v127, v119
	v_mfma_f32_32x32x16_bf16 v[80:95], v[214:217], v[128:131], v[80:95]
	v_add_f32_e32 v96, v112, v96
	v_add_f32_e32 v97, v113, v97
	v_exp_f32_e32 v118, v102
	v_add_f32_e32 v96, v114, v96
	v_add_f32_e32 v97, v115, v97
	v_exp_f32_e32 v119, v103
	v_add_f32_e32 v120, v116, v96
	v_add_f32_e32 v121, v117, v97
	v_exp_f32_e32 v96, v104
	v_exp_f32_e32 v97, v105
	v_mfma_f32_32x32x16_bf16 v[64:79], v[218:221], v[136:139], v[64:79]
	v_exp_f32_e32 v98, v106
	v_exp_f32_e32 v99, v107
	v_exp_f32_e32 v100, v108
	v_exp_f32_e32 v101, v109
	v_add_f32_e32 v102, v118, v120
	v_add_f32_e32 v103, v119, v121
	v_exp_f32_e32 v206, v82
	v_add_f32_e32 v102, v96, v102
	v_add_f32_e32 v103, v97, v103
	v_exp_f32_e32 v207, v83
	v_add_f32_e32 v102, v98, v102
	v_add_f32_e32 v103, v99, v103
	v_mfma_f32_32x32x16_bf16 v[64:79], v[222:225], v[132:135], v[64:79]
	v_add_f32_e32 v104, v100, v102
	v_add_f32_e32 v105, v101, v103
	v_exp_f32_e32 v102, v110
	v_exp_f32_e32 v103, v111
	v_exp_f32_e32 v110, v80
	v_exp_f32_e32 v111, v81
	v_exp_f32_e32 v208, v84
	v_exp_f32_e32 v209, v85
	v_exp_f32_e32 v210, v86
	v_add_f32_e32 v80, 0, v110
	v_add_f32_e32 v81, 0, v111
	v_add_u32_e32 v86, s28, v249
	v_add_f32_e32 v80, v206, v80
	v_add_f32_e32 v81, v207, v81
	v_add_f32_e32 v84, v208, v80
	v_add_f32_e32 v85, v209, v81
	v_add_u32_e32 v80, s28, v248
	ds_read2_b64 v[80:83], v80 offset0:128 offset1:130
	ds_read2_b64 v[106:109], v86 offset0:128 offset1:130
	v_mfma_f32_32x32x16_bf16 v[64:79], v[226:229], v[128:131], v[64:79]
	v_exp_f32_e32 v211, v87
	v_exp_f32_e32 v212, v88
	v_exp_f32_e32 v213, v89
	v_exp_f32_e32 v214, v90
	v_exp_f32_e32 v215, v91
	v_add_f32_e32 v84, v210, v84
	v_add_f32_e32 v85, v211, v85
	v_cvt_pk_bf16_f32 v120, v230, v231
	v_cvt_pk_bf16_f32 v121, v232, v233
	v_cvt_pk_bf16_f32 v122, v234, v235
	v_cvt_pk_bf16_f32 v123, v236, v237
	v_add_f32_e32 v84, v212, v84
	v_add_f32_e32 v85, v213, v85
	v_cvt_pk_bf16_f32 v86, v208, v209
	s_waitcnt lgkmcnt(0)
; __device__ __forceinline__ unsigned pk2(float lo, float hi) { f32x2 v = {lo, hi}; return __builtin_bit_cast(unsigned, __builtin_convertvector(v, bf16v2)); }
; #define LAS __attribute__((address_space(3)))
; __device__ __forceinline__ float ex2(float x) { return __builtin_amdgcn_exp2f(x); }
; template <bool SAFE>
; __device__ void phase_attn(const Params& p, const bf16_t* Qall, const bf16_t* Kall, const bf16_t* Vt, bf16_t* CAT, LAS unsigned char* lds) {
;     ...
;         f32x2 ps2 = {0.f, 0.f};
;         const f32x2 m2 = {mrun[qb], mrun[qb]};
; #pragma unroll
;         for (int kb = 0; kb < 2; ++kb)
; #pragma unroll
;           for (int e = 0; e < 16; e += 2) {
;             f32x2 t = {s[qb][kb][e], s[qb][kb][e + 1]};
;             if (SAFE) t = t - m2;
;             t.x = ex2(t.x); t.y = ex2(t.y);
;             ps2 += t;
;             s[qb][kb][e] = t.x; s[qb][kb][e + 1] = t.y;
;           }
;         lrun[qb] += ps2.x + ps2.y;
;         if (!SAFE) wbad = wbad || !(ps2.x + ps2.y < 1.2089258e24f);
;       }
; #pragma unroll
;       for (int kb = 0; kb < 2; ++kb)
; #pragma unroll
;         for (int t = 0; t < 2; ++t) {
;           const int kofs = 32 * kb + 16 * t + 4 * hh;
;           u32x4 va, vb2;
;           { const u32x2 lo = *(const LAS u32x2*)(vb_ + (r * VROW + kofs) * 2), hi = *(const LAS u32x2*)(vb_ + (r * VROW + kofs + 8) * 2); va.x = lo.x; va.y = lo.y; va.z = hi.x; va.w = hi.y; }
;           { const u32x2 lo = *(const LAS u32x2*)(vb_ + ((32 + r) * VROW + kofs) * 2), hi = *(const LAS u32x2*)(vb_ + ((32 + r) * VROW + kofs + 8) * 2); vb2.x = lo.x; vb2.y = lo.y; vb2.z = hi.x; vb2.w = hi.y; }
; #pragma unroll
;           for (int qb = 0; qb < 2; ++qb) {
;             u32x4 pw;
;             pw.x = pk2(s[qb][kb][8 * t], s[qb][kb][8 * t + 1]); pw.y = pk2(s[qb][kb][8 * t + 2], s[qb][kb][8 * t + 3]);
;             pw.z = pk2(s[qb][kb][8 * t + 4], s[qb][kb][8 * t + 5]); pw.w = pk2(s[qb][kb][8 * t + 6], s[qb][kb][8 * t + 7]);
;             const bf16x8 pf = __builtin_bit_cast(bf16x8, pw);
;             o[qb][0] = __builtin_amdgcn_mfma_f32_32x32x16_bf16(__builtin_bit_cast(bf16x8, va), pf, o[qb][0], 0, 0, 0);
;             o[qb][1] = __builtin_amdgcn_mfma_f32_32x32x16_bf16(__builtin_bit_cast(bf16x8, vb2), pf, o[qb][1], 0, 0, 0);
;           }
;         }
;       asm volatile("s_waitcnt vmcnt(0)" ::: "memory");
;       __syncthreads();
	v_mfma_f32_32x32x16_bf16 v[48:63], v[80:83], v[120:123], v[48:63]
	v_cvt_pk_bf16_f32 v87, v210, v211
	v_exp_f32_e32 v92, v92
	v_exp_f32_e32 v93, v93
	v_exp_f32_e32 v94, v94
	v_exp_f32_e32 v95, v95
	v_cvt_pk_bf16_f32 v88, v238, v239
	v_cvt_pk_bf16_f32 v89, v240, v241
	v_mfma_f32_32x32x16_bf16 v[32:47], v[106:109], v[120:123], v[32:47]
	v_add_f32_e32 v120, v214, v84
	v_add_f32_e32 v121, v215, v85
	v_cvt_pk_bf16_f32 v84, v110, v111
	v_exp_f32_e32 v110, v64
	v_add_u32_e32 v64, s28, v250
	v_cvt_pk_bf16_f32 v85, v206, v207
	v_exp_f32_e32 v111, v65
	v_mfma_f32_32x32x16_bf16 v[16:31], v[80:83], v[84:87], v[16:31]
	ds_read2_b64 v[80:83], v64 offset0:128 offset1:130
	v_add_u32_e32 v64, s28, v251
	v_cvt_pk_bf16_f32 v90, v124, v125
	v_cvt_pk_bf16_f32 v91, v126, v127
	v_add_f32_e32 v104, v102, v104
	v_add_f32_e32 v105, v103, v105
	v_mfma_f32_32x32x16_bf16 v[0:15], v[106:109], v[84:87], v[0:15]
	ds_read2_b64 v[84:87], v64 offset0:128 offset1:130
	v_exp_f32_e32 v106, v66
	v_exp_f32_e32 v107, v67
	v_add_f32_e32 v64, v92, v120
	v_add_f32_e32 v65, v93, v121
	v_exp_f32_e32 v120, v68
	v_exp_f32_e32 v121, v69
	v_add_f32_e32 v64, v94, v64
	v_add_f32_e32 v65, v95, v65
	s_waitcnt lgkmcnt(0)
	v_mfma_f32_32x32x16_bf16 v[48:63], v[80:83], v[88:91], v[48:63]
	v_add_f32_e32 v64, v110, v64
	v_add_f32_e32 v65, v111, v65
	v_cvt_pk_bf16_f32 v66, v92, v93
	v_add_f32_e32 v108, v106, v64
	v_add_f32_e32 v109, v107, v65
	v_cvt_pk_bf16_f32 v64, v212, v213
	v_add_f32_e32 v68, v120, v108
	v_add_f32_e32 v69, v121, v109
	v_cvt_pk_bf16_f32 v65, v214, v215
	v_cvt_pk_bf16_f32 v67, v94, v95
	v_mfma_f32_32x32x16_bf16 v[32:47], v[84:87], v[88:91], v[32:47]
	v_exp_f32_e32 v88, v70
	v_exp_f32_e32 v89, v71
	v_exp_f32_e32 v92, v72
	v_exp_f32_e32 v93, v73
	v_add_f32_e32 v90, v88, v68
	v_add_f32_e32 v91, v89, v69
	v_add_u32_e32 v68, s28, v252
	v_mfma_f32_32x32x16_bf16 v[16:31], v[80:83], v[64:67], v[16:31]
	ds_read2_b64 v[68:71], v68 offset0:128 offset1:130
	v_add_f32_e32 v72, v92, v90
	v_add_f32_e32 v73, v93, v91
	v_exp_f32_e32 v90, v78
	v_exp_f32_e32 v91, v79
	v_cvt_pk_bf16_f32 v80, v112, v113
	v_cvt_pk_bf16_f32 v81, v114, v115
	v_mfma_f32_32x32x16_bf16 v[0:15], v[84:87], v[64:67], v[0:15]
	v_add_u32_e32 v64, s28, v253
	ds_read2_b64 v[64:67], v64 offset0:128 offset1:130
	v_exp_f32_e32 v84, v74
	v_exp_f32_e32 v85, v75
	v_exp_f32_e32 v86, v76
	v_exp_f32_e32 v87, v77
	v_cvt_pk_bf16_f32 v82, v116, v117
	v_add_f32_e32 v72, v84, v72
	v_add_f32_e32 v73, v85, v73
	v_cvt_pk_bf16_f32 v83, v118, v119
	v_add_f32_e32 v72, v86, v72
	v_add_f32_e32 v73, v87, v73
	v_cvt_pk_bf16_f32 v74, v120, v121
	v_add_f32_e32 v76, v90, v72
	v_add_f32_e32 v77, v91, v73
	v_cvt_pk_bf16_f32 v72, v110, v111
	v_cvt_pk_bf16_f32 v73, v106, v107
	v_cvt_pk_bf16_f32 v75, v88, v89
	s_waitcnt lgkmcnt(0)
	v_mfma_f32_32x32x16_bf16 v[48:63], v[68:71], v[80:83], v[48:63]
	v_cvt_pk_bf16_f32 v78, v86, v87
	v_cvt_pk_bf16_f32 v79, v90, v91
	v_mfma_f32_32x32x16_bf16 v[16:31], v[68:71], v[72:75], v[16:31]
	v_add_f32_e32 v76, v76, v77
	v_add_f32_e32 v77, v104, v105
	v_add_u32_e32 v68, s28, v254
	ds_read2_b64 v[68:71], v68 offset0:128 offset1:130
	v_mfma_f32_32x32x16_bf16 v[32:47], v[64:67], v[80:83], v[32:47]
	v_cmp_ngt_f32_e32 vcc, s44, v77
	v_add_f32_e32 v194, v194, v76
	v_add_f32_e32 v195, v195, v77
	v_cvt_pk_bf16_f32 v77, v84, v85
	v_mfma_f32_32x32x16_bf16 v[0:15], v[64:67], v[72:75], v[0:15]
	v_add_u32_e32 v64, s28, v255
	ds_read2_b64 v[64:67], v64 offset0:128 offset1:130
	v_cvt_pk_bf16_f32 v72, v96, v97
	v_cvt_pk_bf16_f32 v73, v98, v99
	v_cvt_pk_bf16_f32 v74, v100, v101
	v_cvt_pk_bf16_f32 v75, v102, v103
	s_or_b64 s[28:29], s[26:27], vcc
	v_cmp_ngt_f32_e32 vcc, s44, v76
	v_cvt_pk_bf16_f32 v76, v92, v93
	s_waitcnt lgkmcnt(0)
	v_mfma_f32_32x32x16_bf16 v[48:63], v[68:71], v[72:75], v[48:63]
	s_or_b64 s[28:29], s[28:29], vcc
	s_add_u32 s4, s4, 0x3000
	s_addc_u32 s5, s5, 0
	s_add_u32 s15, s15, 0x80
	s_waitcnt vmcnt(0)
	s_addc_u32 s49, s49, 0
	s_andn2_b64 s[26:27], s[26:27], exec
	v_mfma_f32_32x32x16_bf16 v[32:47], v[64:67], v[72:75], v[32:47]
	s_and_b64 s[52:53], s[28:29], exec
	s_or_b64 s[26:27], s[26:27], s[52:53]
	s_cmp_eq_u32 s1, s50
	s_waitcnt vmcnt(0)
	s_barrier
	v_mfma_f32_32x32x16_bf16 v[16:31], v[68:71], v[76:79], v[16:31]
	v_mfma_f32_32x32x16_bf16 v[0:15], v[64:67], v[76:79], v[0:15]
	s_cbranch_scc1 .LBB0_1261
